# mirror A/B of the static priority raise: s_setprio 1 for the older wave half (waves 0-3) over the phase-8 gla_c item loop
# baseline (speedup 1.0000x reference)
; __device__ __forceinline__ void gla_c_item(const Params& P, int item, unsigned char* smem) {
;     float* sGLR = (float*)smem;
;     float* sPart = (float*)(smem + 8192);
;     bf16_t* sQD = (bf16_t*)(smem + 10240);
;     bf16_t* sKD = (bf16_t*)(smem + 10240 + 9216);
;     bf16_t* sQG = (bf16_t*)(smem + 10240 + 2 * 9216);
;     bf16_t* sP = (bf16_t*)(smem + 10240 + 2 * 9216 + 17408);
;     bf16_t* sVt = (bf16_t*)(smem + 10240 + 3 * 9216 + 17408);
;     const int m = item & 127, h = (item >> 7) & 3, b = item >> 9;
;     const int rowbase = b * 8192 + m * 64;
;     const bf16_t* Q = (const bf16_t*)(P.ws + OFF_Q); const bf16_t* Kb = (const bf16_t*)(P.ws + OFF_K);
;     bf16_t* V = (bf16_t*)(P.ws + OFF_V); const bf16_t* R = (const bf16_t*)(P.ws + OFF_R); const bf16_t* GLR = (const bf16_t*)(P.ws + OFF_GLR);
;     const int tid = threadIdx.x & 255, lane = tid & 63, w = tid >> 6, fr = lane & 15, fq = lane >> 4, dk = tid & 63, part = tid >> 6;
;     const VRegs vr = load_v_regs(V + (size_t)rowbase * 512 + h * 128, tid);
;     const uint4 gl8 = *(const uint4*)(GLR + (size_t)(rowbase + (tid >> 2)) * 32 + (tid & 3) * 8);
;     float qq[16], kk[16];
; #pragma unroll
;     for (int ii = 0; ii < 16; ++ii) { qq[ii] = bf2f(Q[(size_t)(rowbase + part * 16 + ii) * 256 + h * 64 + dk]); kk[ii] = bf2f(Kb[(size_t)(rowbase + part * 16 + ii) * 256 + h * 64 + dk]); }
;     const GateW gw0 = load_gate_w(P, 0, h, dk), gw1 = load_gate_w(P, 1, h, dk);
;     {
;         float* gp = sGLR + (tid >> 2) * 32 + (tid & 3) * 8;
;         *(f32x4*)gp = (f32x4){bflo(gl8.x), bfhi(gl8.x), bflo(gl8.y), bfhi(gl8.y)};
;         *(f32x4*)(gp + 4) = (f32x4){bflo(gl8.z), bfhi(gl8.z), bflo(gl8.w), bfhi(gl8.w)};
;     }
;     store_vt(vr, sVt, tid);
;     __syncthreads();
;     float gc0[16], gc1[16];
;     { const float tot0 = gate_prefix(gw0, sGLR, 32, 0, part, gc0); const float tot1 = gate_prefix(gw1, sGLR + 16, 32, 1, part, gc1);
;       sPart[part * 64 + dk] = tot0; sPart[256 + part * 64 + dk] = tot1; }
;     __syncthreads();
;     float gref0, gref1;
;     {
;         const float a0 = sPart[dk], a1 = sPart[64 + dk], a2 = sPart[128 + dk];
;         const float c1 = sPart[256 + 64 + dk], c2 = sPart[256 + 128 + dk], c3 = sPart[256 + 192 + dk];
;         const float off0 = part == 0 ? 0.f : (part == 1 ? a0 : (part == 2 ? a0 + a1 : a0 + a1 + a2));
.LBB0_1317:
.LBB0_1318:
	v_lshlrev_b32_e32 v4, 3, v168
	v_lshrrev_b32_e32 v88, 8, v168
	s_mov_b32 s0, 0x13800
	v_bfe_u32 v90, v168, 2, 6
	v_and_b32_e32 v5, 24, v4
	s_waitcnt lgkmcnt(0)
	v_mad_u32_u24 v1, v88, s0, 16
	v_lshrrev_b32_e32 v75, 1, v168
	v_lshlrev_b32_e32 v4, 7, v90
	v_lshlrev_b32_e32 v6, 2, v5
	v_bfe_u32 v89, v168, 6, 2
	v_and_b32_e32 v2, 0x70, v75
	v_add3_u32 v92, v1, v4, v6
	v_lshlrev_b32_e32 v6, 2, v168
	v_lshlrev_b32_e32 v91, 4, v89
	v_mul_u32_u24_e32 v4, 0x90, v2
	v_and_b32_e32 v6, 0x7c, v6
	v_and_b32_e32 v169, 15, v168
	v_and_b32_e32 v3, 0xff, v168
	v_add3_u32 v93, v1, v4, v6
	v_or_b32_e32 v97, v91, v169
	v_and_b32_e32 v4, 48, v168
	v_lshl_add_u32 v95, v3, 2, v1
	v_cmp_lt_u32_e64 s[74:75], 63, v3
	v_mul_u32_u24_e32 v3, 0x48, v97
	v_add_u32_e32 v7, v1, v4
	v_lshl_add_u32 v98, v3, 1, v7
	v_mul_u32_u24_e32 v3, 0x480, v89
	v_lshl_add_u32 v96, v170, 2, v1
	v_or_b32_e32 v3, v3, v170
	v_lshlrev_b32_e32 v6, 1, v170
	v_lshl_add_u32 v99, v3, 1, v1
	v_mul_u32_u24_e32 v3, 0x880, v89
	v_sub_u32_e32 v6, v96, v6
	v_lshl_add_u32 v100, v3, 1, v6
	v_or_b32_e32 v3, 1, v91
	v_mul_u32_u24_e32 v8, 0x48, v3
	v_lshl_add_u32 v101, v8, 1, v6
	v_mul_u32_u24_e32 v8, 0x88, v3
	s_movk_i32 s0, 0x48
	v_lshl_add_u32 v102, v8, 1, v6
	v_mov_b32_e32 v8, 0x1f8
	v_mad_u32_u24 v3, v3, s0, v8
	v_lshrrev_b32_e32 v10, 2, v168
	v_or_b32_e32 v8, v3, v170
	v_lshl_add_u32 v3, v3, 1, v6
	v_and_b32_e32 v6, 12, v10
	v_or_b32_e32 v11, v91, v6
	v_writelane_b32 v251, s88, 54
	v_or_b32_e32 v9, 48, v169
	v_or_b32_e32 v13, 2, v11
	v_writelane_b32 v251, s89, 55
	v_cmp_lt_u32_e64 s[2:3], v9, v13
	v_or_b32_e32 v15, 1, v11
	s_add_u32 s78, s68, 0xd0bd000
	v_writelane_b32 v251, s2, 5
	v_lshl_add_u32 v115, v8, 1, v1
	v_or_b32_e32 v8, 32, v169
	v_writelane_b32 v251, s3, 6
	v_cmp_gt_u32_e64 s[2:3], v9, v13
	v_or_b32_e32 v12, 3, v11
	s_addc_u32 s79, s69, 0
	v_writelane_b32 v251, s2, 56
	s_add_u32 s80, s68, 0xe13d000
	v_add_u32_e32 v117, 0x90, v3
	v_writelane_b32 v251, s3, 57
	v_cmp_gt_u32_e64 s[2:3], v9, v15
	v_add_u32_e32 v119, 0x120, v3
	v_add_u32_e32 v121, 0x1b0, v3
	v_writelane_b32 v251, s2, 58
	v_add_u32_e32 v123, 0x240, v3
	v_add_u32_e32 v125, 0x2d0, v3
	v_writelane_b32 v251, s3, 59
	v_cmp_lt_u32_e64 s[2:3], v9, v11
	v_add_u32_e32 v127, 0x360, v3
	v_add_u32_e32 v129, 0x3f0, v3
	v_writelane_b32 v251, s2, 60
	v_mul_u32_u24_e32 v3, 0x48, v169
	s_addc_u32 s81, s69, 0
	v_writelane_b32 v251, s3, 61
	v_cmp_lt_u32_e64 s[2:3], v8, v12
	v_lshl_add_u32 v131, v3, 1, v7
	v_or_b32_e32 v3, 16, v169
	v_writelane_b32 v251, s2, 62
	s_add_u32 s82, s68, 0xf1bd000
	v_cmp_lt_u32_e64 s[30:31], v3, v12
	v_writelane_b32 v251, s3, 63
	v_cmp_gt_u32_e64 s[2:3], v8, v12
	v_cmp_gt_u32_e64 s[34:35], v3, v12
	v_cmp_lt_u32_e64 s[36:37], v3, v13
	v_writelane_b32 v250, s2, 0
	v_cmp_gt_u32_e64 s[38:39], v3, v13
	v_cmp_gt_u32_e64 s[40:41], v3, v11
	v_cmp_gt_u32_e64 s[42:43], v3, v15
	v_cmp_lt_u32_e64 s[44:45], v3, v11
	v_mul_u32_u24_e32 v3, 0x48, v11
	s_addc_u32 s83, s69, 0
	v_lshlrev_b32_e32 v0, 10, v168
	v_mov_b32_e32 v37, 0
	s_movk_i32 s1, 0x110
	v_writelane_b32 v250, s3, 1
	v_cmp_lt_u32_e64 s[2:3], v8, v13
	v_cmp_gt_u32_e64 s[6:7], v8, v13
	v_cmp_gt_u32_e64 s[24:25], v8, v11
	v_cmp_gt_u32_e64 s[26:27], v8, v15
	v_cmp_lt_u32_e64 s[28:29], v8, v11
	v_lshlrev_b32_e32 v8, 1, v169
	v_lshlrev_b32_e32 v3, 1, v3
	v_lshlrev_b32_e32 v36, 1, v5
	s_add_u32 s84, s68, 0x112bd000
	v_and_b32_e32 v0, 0x7c00, v0
	v_lshl_add_u32 v94, v89, 11, v1
	v_add3_u32 v132, v1, v8, v3
	v_and_or_b32 v1, v10, 64, v97
	v_mad_u32_u24 v137, v97, s1, v7
	v_lshlrev_b32_e32 v8, 6, v169
	v_lshl_add_u64 v[22:23], s[68:69], 0, v[36:37]
	s_mov_b64 s[0:1], 0x133bd000
	s_addc_u32 s85, s69, 0
	v_mov_b32_e32 v5, v37
	v_readlane_b32 s8, v251, 37
	v_cmp_lt_u32_e64 s[86:87], v9, v12
	v_cmp_gt_u32_e64 s[94:95], v9, v12
	v_writelane_b32 v250, s2, 2
	v_cmp_lt_u32_e64 s[46:47], v169, v12
	v_cmp_gt_u32_e64 s[48:49], v169, v12
	v_lshlrev_b32_e32 v136, 6, v1
	v_or_b32_e32 v10, 0x800, v8
	v_or_b32_e32 v12, 0xc00, v8
	v_or_b32_e32 v14, 0x1000, v8
	v_or_b32_e32 v16, 0x1400, v8
	v_or_b32_e32 v18, 0x1800, v8
	v_or_b32_e32 v20, 0x1c00, v8
	v_lshlrev_b32_e32 v1, 7, v97
	s_waitcnt vmcnt(0)
	v_lshl_add_u64 v[38:39], v[22:23], 0, s[0:1]
	s_add_u32 s88, s68, 0x18c3d000
	v_lshl_add_u64 v[22:23], s[68:69], 0, v[4:5]
	s_mov_b64 s[0:1], 0x52bd000
	v_readlane_b32 s10, v251, 39
	v_readlane_b32 s11, v251, 40
	v_lshlrev_b32_e32 v44, 1, v0
	v_mbcnt_lo_u32_b32 v0, -1, 0
	v_add_u32_e32 v103, 0x90, v101
	v_add_u32_e32 v104, 0x110, v102
	v_add_u32_e32 v105, 0x120, v101
	v_add_u32_e32 v106, 0x220, v102
	v_add_u32_e32 v107, 0x1b0, v101
	v_add_u32_e32 v108, 0x330, v102
	v_add_u32_e32 v109, 0x240, v101
	v_add_u32_e32 v110, 0x440, v102
	v_add_u32_e32 v111, 0x2d0, v101
	v_add_u32_e32 v112, 0x550, v102
	v_add_u32_e32 v113, 0x360, v101
	v_add_u32_e32 v114, 0x660, v102
	v_add_u32_e32 v116, 0x770, v102
	v_add_u32_e32 v118, 0x880, v102
	v_add_u32_e32 v120, 0x990, v102
	v_add_u32_e32 v122, 0xaa0, v102
	v_add_u32_e32 v124, 0xbb0, v102
	v_add_u32_e32 v126, 0xcc0, v102
	v_add_u32_e32 v128, 0xdd0, v102
	v_add_u32_e32 v130, 0xee0, v102
	v_cmp_gt_u32_e32 vcc, v9, v11
	v_writelane_b32 v250, s3, 3
	v_cmp_lt_u32_e64 s[50:51], v169, v13
	v_cmp_gt_u32_e64 s[52:53], v169, v13
	v_cmp_gt_u32_e64 s[54:55], v169, v11
	v_add_u32_e32 v133, 0x90, v132
	v_add_u32_e32 v134, 0x120, v132
	v_add_u32_e32 v135, 0x1b0, v132
	v_sub_u32_e32 v138, v137, v1
	v_add_u32_e32 v139, 0xd800, v131
	v_add_u32_e32 v140, 0xd840, v131
	s_addc_u32 s89, s69, 0
	s_lshl_b32 s76, s90, 1
	v_lshl_add_u64 v[40:41], v[22:23], 0, s[0:1]
	v_lshl_add_u64 v[42:43], s[10:11], 0, v[4:5]
	v_lshlrev_b32_e32 v46, 1, v2
	s_mov_b32 s72, 0xffff0000
	s_mov_b32 s73, 0xbfb8aa3b
	s_mov_b32 s2, 0x800000
	s_mov_b32 s3, 0x3f317217
	v_lshlrev_b32_e32 v48, 1, v6
	v_lshlrev_b32_e32 v50, 1, v8
	v_lshlrev_b32_e32 v52, 1, v10
	v_lshlrev_b32_e32 v54, 1, v12
	v_lshlrev_b32_e32 v56, 1, v14
	v_lshlrev_b32_e32 v58, 1, v16
	v_lshlrev_b32_e32 v60, 1, v18
	v_lshlrev_b32_e32 v62, 1, v20
	v_mbcnt_hi_u32_b32 v141, -1, v0
	v_mov_b32_e32 v142, 0x358637bd
	v_mov_b32_e32 v143, 0x41b17218
	s_mov_b32 s4, 0x7f800000
	v_cmp_gt_u32_e64 s[56:57], v169, v15
	v_cmp_lt_u32_e64 s[58:59], v169, v11
	v_readlane_b32 s9, v251, 38
	v_readlane_b32 s12, v251, 41
	v_readlane_b32 s13, v251, 42
	v_readlane_b32 s14, v251, 43
	v_readlane_b32 s15, v251, 44
	v_readlane_b32 s16, v251, 45
	v_readlane_b32 s17, v251, 46
	v_readlane_b32 s18, v251, 47
	v_readlane_b32 s19, v251, 48
	v_readlane_b32 s20, v251, 49
	v_readlane_b32 s21, v251, 50
	v_readlane_b32 s22, v251, 51
	v_readlane_b32 s23, v251, 52
	v_readfirstlane_b32 s98, v171
	s_nop 3
	s_cmp_ge_u32 s98, 4
	s_cbranch_scc1 .Lprio8_done
	s_setprio 1
